# residual+rmsnorm phases: loads of all four rows of a round issued before the first wait (per-row 1/scale loads in own registers), unpack blocks after one vmcnt(0)
# baseline (speedup 1.0000x reference)
.LBB0_576:
	s_ashr_i32 s13, s12, 31
	s_lshl_b64 s[22:23], s[12:13], 11
	s_lshl_b64 s[24:25], s[12:13], 2
	s_add_u32 s14, s28, s24
	v_lshl_add_u64 v[120:121], v[68:69], 0, s[22:23]
	s_addc_u32 s15, s29, s25
	global_load_dword v64, v65, s[14:15]
	global_load_dwordx2 v[126:127], v[120:121], off nt
	global_load_dwordx2 v[124:125], v[120:121], off offset:512 nt
	global_load_dwordx2 v[122:123], v[120:121], off offset:1024 nt
	s_nop 0
	global_load_dwordx2 v[120:121], v[120:121], off offset:1536 nt
	v_lshl_add_u64 v[128:129], v[66:67], 0, s[22:23]
	global_load_dwordx2 v[134:135], v[128:129], off nt
	global_load_dwordx2 v[132:133], v[128:129], off offset:512 nt
	global_load_dwordx2 v[130:131], v[128:129], off offset:1024 nt
	s_nop 0
	global_load_dwordx2 v[128:129], v[128:129], off offset:1536 nt
	s_add_i32 s10, s12, s6
	s_cmp_lt_i32 s10, s98
	s_cselect_b64 s[20:21], -1, 0
	s_cmp_ge_i32 s10, s98
	s_cbranch_scc1 .LBB0_578
	s_ashr_i32 s11, s10, 31
	s_lshl_b64 s[16:17], s[10:11], 11
	v_lshl_add_u64 v[40:41], v[68:69], 0, s[16:17]
	s_add_u32 s14, s14, s8
	global_load_dwordx2 v[42:43], v[40:41], off nt
	global_load_dwordx2 v[48:49], v[40:41], off offset:512 nt
	global_load_dwordx2 v[50:51], v[40:41], off offset:1024 nt
	s_nop 0
	global_load_dwordx2 v[40:41], v[40:41], off offset:1536 nt
	v_lshl_add_u64 v[56:57], v[66:67], 0, s[16:17]
	s_addc_u32 s15, s15, s9
	global_load_dwordx2 v[58:59], v[56:57], off nt
	global_load_dwordx2 v[60:61], v[56:57], off offset:512 nt
	global_load_dwordx2 v[62:63], v[56:57], off offset:1024 nt
	global_load_dwordx2 v[118:119], v[56:57], off offset:1536 nt
	global_load_dword v208, v65, s[14:15]
.LBB0_578:
	s_add_i32 s14, s34, s12
	s_cmp_lt_i32 s14, s98
	s_cselect_b64 s[18:19], -1, 0
	s_cmp_ge_i32 s14, s98
	s_cbranch_scc1 .LBB0_580
	s_ashr_i32 s15, s14, 31
	s_lshl_b64 s[16:17], s[14:15], 11
	v_lshl_add_u64 v[32:33], v[68:69], 0, s[16:17]
	v_lshl_add_u64 v[44:45], v[66:67], 0, s[16:17]
	s_lshl_b64 s[16:17], s[14:15], 2
	s_add_u32 s16, s28, s16
	global_load_dwordx2 v[34:35], v[32:33], off nt
	global_load_dwordx2 v[36:37], v[32:33], off offset:512 nt
	global_load_dwordx2 v[38:39], v[32:33], off offset:1024 nt
	s_nop 0
	global_load_dwordx2 v[32:33], v[32:33], off offset:1536 nt
	s_addc_u32 s17, s29, s17
	global_load_dwordx2 v[46:47], v[44:45], off nt
	global_load_dwordx2 v[52:53], v[44:45], off offset:512 nt
	global_load_dwordx2 v[54:55], v[44:45], off offset:1024 nt
	global_load_dwordx2 v[116:117], v[44:45], off offset:1536 nt
	global_load_dword v210, v65, s[16:17]
.LBB0_580:
	s_add_i32 s12, s35, s12
	s_cmp_lt_i32 s12, s98
	s_cselect_b64 s[16:17], -1, 0
	s_cmp_ge_i32 s12, s98
	s_cbranch_scc1 .Lrl_576_w
	s_ashr_i32 s13, s12, 31
	s_lshl_b64 s[26:27], s[12:13], 11
	v_lshl_add_u64 v[16:17], v[68:69], 0, s[26:27]
	v_lshl_add_u64 v[24:25], v[66:67], 0, s[26:27]
	s_lshl_b64 s[26:27], s[12:13], 2
	s_add_u32 s26, s28, s26
	global_load_dwordx2 v[18:19], v[16:17], off nt
	global_load_dwordx2 v[20:21], v[16:17], off offset:512 nt
	global_load_dwordx2 v[22:23], v[16:17], off offset:1024 nt
	s_nop 0
	global_load_dwordx2 v[16:17], v[16:17], off offset:1536 nt
	s_addc_u32 s27, s29, s27
	global_load_dwordx2 v[26:27], v[24:25], off nt
	global_load_dwordx2 v[28:29], v[24:25], off offset:512 nt
	global_load_dwordx2 v[30:31], v[24:25], off offset:1024 nt
	global_load_dwordx2 v[108:109], v[24:25], off offset:1536 nt
	global_load_dword v212, v65, s[26:27]
.Lrl_576_w:
	s_waitcnt vmcnt(0)
	s_cmp_lg_u64 s[20:21], 0
	s_cbranch_scc0 .Lrl_576_u1
	v_lshlrev_b32_e32 v56, 16, v42
	v_and_b32_e32 v57, 0xffff0000, v42
	v_lshlrev_b32_e32 v42, 16, v43
	v_and_b32_e32 v43, 0xffff0000, v43
	v_lshlrev_b32_e32 v146, 16, v48
	v_and_b32_e32 v147, 0xffff0000, v48
	v_lshlrev_b32_e32 v48, 16, v49
	v_and_b32_e32 v49, 0xffff0000, v49
	v_lshlrev_b32_e32 v148, 16, v50
	v_and_b32_e32 v149, 0xffff0000, v50
	v_lshlrev_b32_e32 v150, 16, v51
	v_and_b32_e32 v151, 0xffff0000, v51
	v_lshlrev_b32_e32 v152, 16, v40
	v_and_b32_e32 v153, 0xffff0000, v40
	v_lshlrev_b32_e32 v154, 16, v41
	v_and_b32_e32 v155, 0xffff0000, v41
	v_lshlrev_b32_e32 v94, 16, v58
	v_and_b32_e32 v95, 0xffff0000, v58
	v_lshlrev_b32_e32 v104, 16, v59
	v_and_b32_e32 v105, 0xffff0000, v59
	v_lshlrev_b32_e32 v92, 16, v60
	v_and_b32_e32 v93, 0xffff0000, v60
	v_lshlrev_b32_e32 v110, 16, v61
	v_and_b32_e32 v111, 0xffff0000, v61
	v_lshlrev_b32_e32 v90, 16, v62
	v_and_b32_e32 v91, 0xffff0000, v62
	v_lshlrev_b32_e32 v114, 16, v63
	v_and_b32_e32 v115, 0xffff0000, v63
	v_lshlrev_b32_e32 v88, 16, v118
	v_and_b32_e32 v89, 0xffff0000, v118
	v_lshlrev_b32_e32 v118, 16, v119
	v_pk_mul_f32 v[42:43], v[208:209], v[42:43] op_sel_hi:[0,1]
	v_pk_mul_f32 v[40:41], v[208:209], v[56:57] op_sel_hi:[0,1]
	v_pk_mul_f32 v[50:51], v[208:209], v[48:49] op_sel_hi:[0,1]
	v_pk_mul_f32 v[48:49], v[208:209], v[146:147] op_sel_hi:[0,1]
	v_pk_mul_f32 v[58:59], v[208:209], v[150:151] op_sel_hi:[0,1]
	v_pk_mul_f32 v[56:57], v[208:209], v[148:149] op_sel_hi:[0,1]
	v_pk_mul_f32 v[62:63], v[208:209], v[154:155] op_sel_hi:[0,1]
	v_pk_mul_f32 v[60:61], v[208:209], v[152:153] op_sel_hi:[0,1]
	v_and_b32_e32 v119, 0xffff0000, v119
.Lrl_576_u1:
	s_cmp_lg_u64 s[18:19], 0
	s_cbranch_scc0 .Lrl_576_u2
	v_lshlrev_b32_e32 v44, 16, v34
	v_and_b32_e32 v45, 0xffff0000, v34
	v_lshlrev_b32_e32 v34, 16, v35
	v_and_b32_e32 v35, 0xffff0000, v35
	v_lshlrev_b32_e32 v146, 16, v36
	v_and_b32_e32 v147, 0xffff0000, v36
	v_lshlrev_b32_e32 v36, 16, v37
	v_and_b32_e32 v37, 0xffff0000, v37
	v_lshlrev_b32_e32 v148, 16, v38
	v_and_b32_e32 v149, 0xffff0000, v38
	v_lshlrev_b32_e32 v150, 16, v39
	v_and_b32_e32 v151, 0xffff0000, v39
	v_lshlrev_b32_e32 v152, 16, v32
	v_and_b32_e32 v153, 0xffff0000, v32
	v_lshlrev_b32_e32 v154, 16, v33
	v_and_b32_e32 v155, 0xffff0000, v33
	v_lshlrev_b32_e32 v86, 16, v46
	v_and_b32_e32 v87, 0xffff0000, v46
	v_lshlrev_b32_e32 v100, 16, v47
	v_and_b32_e32 v101, 0xffff0000, v47
	v_lshlrev_b32_e32 v84, 16, v52
	v_and_b32_e32 v85, 0xffff0000, v52
	v_lshlrev_b32_e32 v106, 16, v53
	v_and_b32_e32 v107, 0xffff0000, v53
	v_lshlrev_b32_e32 v82, 16, v54
	v_and_b32_e32 v83, 0xffff0000, v54
	v_lshlrev_b32_e32 v112, 16, v55
	v_and_b32_e32 v113, 0xffff0000, v55
	v_lshlrev_b32_e32 v80, 16, v116
	v_and_b32_e32 v81, 0xffff0000, v116
	v_lshlrev_b32_e32 v116, 16, v117
	v_pk_mul_f32 v[34:35], v[210:211], v[34:35] op_sel_hi:[0,1]
	v_pk_mul_f32 v[32:33], v[210:211], v[44:45] op_sel_hi:[0,1]
	v_pk_mul_f32 v[38:39], v[210:211], v[36:37] op_sel_hi:[0,1]
	v_pk_mul_f32 v[36:37], v[210:211], v[146:147] op_sel_hi:[0,1]
	v_pk_mul_f32 v[46:47], v[210:211], v[150:151] op_sel_hi:[0,1]
	v_pk_mul_f32 v[44:45], v[210:211], v[148:149] op_sel_hi:[0,1]
	v_pk_mul_f32 v[54:55], v[210:211], v[154:155] op_sel_hi:[0,1]
	v_pk_mul_f32 v[52:53], v[210:211], v[152:153] op_sel_hi:[0,1]
	v_and_b32_e32 v117, 0xffff0000, v117
.Lrl_576_u2:
	s_cmp_lg_u64 s[16:17], 0
	s_cbranch_scc0 .Lrl_576_u3
	v_lshlrev_b32_e32 v24, 16, v18
	v_and_b32_e32 v25, 0xffff0000, v18
	v_lshlrev_b32_e32 v18, 16, v19
	v_and_b32_e32 v19, 0xffff0000, v19
	v_lshlrev_b32_e32 v146, 16, v20
	v_and_b32_e32 v147, 0xffff0000, v20
	v_lshlrev_b32_e32 v20, 16, v21
	v_and_b32_e32 v21, 0xffff0000, v21
	v_lshlrev_b32_e32 v148, 16, v22
	v_and_b32_e32 v149, 0xffff0000, v22
	v_lshlrev_b32_e32 v150, 16, v23
	v_and_b32_e32 v151, 0xffff0000, v23
	v_lshlrev_b32_e32 v152, 16, v16
	v_and_b32_e32 v153, 0xffff0000, v16
	v_lshlrev_b32_e32 v154, 16, v17
	v_and_b32_e32 v155, 0xffff0000, v17
	v_lshlrev_b32_e32 v78, 16, v26
	v_and_b32_e32 v79, 0xffff0000, v26
	v_lshlrev_b32_e32 v96, 16, v27
	v_and_b32_e32 v97, 0xffff0000, v27
	v_lshlrev_b32_e32 v76, 16, v28
	v_and_b32_e32 v77, 0xffff0000, v28
	v_lshlrev_b32_e32 v98, 16, v29
	v_and_b32_e32 v99, 0xffff0000, v29
	v_lshlrev_b32_e32 v74, 16, v30
	v_and_b32_e32 v75, 0xffff0000, v30
	v_lshlrev_b32_e32 v102, 16, v31
	v_and_b32_e32 v103, 0xffff0000, v31
	v_lshlrev_b32_e32 v72, 16, v108
	v_and_b32_e32 v73, 0xffff0000, v108
	v_lshlrev_b32_e32 v108, 16, v109
	v_pk_mul_f32 v[18:19], v[212:213], v[18:19] op_sel_hi:[0,1]
	v_pk_mul_f32 v[16:17], v[212:213], v[24:25] op_sel_hi:[0,1]
	v_pk_mul_f32 v[22:23], v[212:213], v[20:21] op_sel_hi:[0,1]
	v_pk_mul_f32 v[20:21], v[212:213], v[146:147] op_sel_hi:[0,1]
	v_pk_mul_f32 v[26:27], v[212:213], v[150:151] op_sel_hi:[0,1]
	v_pk_mul_f32 v[24:25], v[212:213], v[148:149] op_sel_hi:[0,1]
	v_pk_mul_f32 v[30:31], v[212:213], v[154:155] op_sel_hi:[0,1]
	v_pk_mul_f32 v[28:29], v[212:213], v[152:153] op_sel_hi:[0,1]
	v_and_b32_e32 v109, 0xffff0000, v109
.Lrl_576_u3:
.LBB0_582:
	s_waitcnt vmcnt(0)
	v_lshlrev_b32_e32 v144, 16, v134
	v_and_b32_e32 v145, 0xffff0000, v134
	v_lshlrev_b32_e32 v134, 16, v135
	v_and_b32_e32 v135, 0xffff0000, v135
	v_lshlrev_b32_e32 v147, 16, v133
	v_lshlrev_b32_e32 v146, 16, v132
	v_and_b32_e32 v133, 0xffff0000, v133
	v_and_b32_e32 v132, 0xffff0000, v132
	v_lshlrev_b32_e32 v151, 16, v128
	v_and_b32_e32 v153, 0xffff0000, v128
	v_mul_f32_e32 v128, v135, v135
	v_mul_f32_e32 v150, v145, v145
	v_lshlrev_b32_e32 v154, 16, v129
	v_and_b32_e32 v155, 0xffff0000, v129
	v_pk_fma_f32 v[128:129], v[134:135], v[134:135], v[128:129] op_sel_hi:[1,1,0]
	v_pk_mul_f32 v[156:157], v[132:133], v[132:133]
	v_pk_fma_f32 v[158:159], v[144:145], v[144:145], v[150:151] op_sel_hi:[1,1,0]
	v_pk_fma_f32 v[156:157], v[146:147], v[146:147], v[156:157]
	v_mov_b32_e32 v150, v158
	v_mov_b32_e32 v160, v128
	v_mov_b32_e32 v161, v151
	v_and_b32_e32 v149, 0xffff0000, v130
	v_mul_f32_e32 v143, v153, v153
	v_pk_add_f32 v[128:129], v[158:159], v[128:129]
	v_pk_mul_f32 v[158:159], v[150:151], v[160:161]
	v_pk_add_f32 v[156:157], v[156:157], v[156:157] op_sel:[0,1] op_sel_hi:[1,0]
	v_lshlrev_b32_e32 v148, 16, v130
	v_lshlrev_b32_e32 v130, 16, v131
	v_and_b32_e32 v131, 0xffff0000, v131
	v_mov_b32_e32 v129, v159
	v_mov_b32_e32 v157, v143
	v_mul_f32_e32 v150, v149, v149
	v_pk_add_f32 v[128:129], v[128:129], v[156:157]
	v_pk_fma_f32 v[156:157], v[148:149], v[148:149], v[150:151] op_sel_hi:[1,1,0]
	v_mul_f32_e32 v150, v131, v131
	v_mul_f32_e32 v152, v154, v154
	v_mul_f32_e32 v162, v155, v155
	v_pk_fma_f32 v[158:159], v[130:131], v[130:131], v[150:151] op_sel_hi:[1,1,0]
	v_mov_b32_e32 v157, v152
	v_mov_b32_e32 v159, v162
	v_pk_add_f32 v[156:157], v[156:157], v[158:159]
	v_lshlrev_b32_e32 v158, 16, v122
	v_pk_add_f32 v[128:129], v[128:129], v[156:157]
	v_and_b32_e32 v159, 0xffff0000, v122
	v_add_f32_e32 v128, v128, v129
	v_lshlrev_b32_e32 v160, 16, v123
	v_and_b32_e32 v161, 0xffff0000, v123
	v_lshlrev_b32_e32 v162, 16, v120
	v_and_b32_e32 v163, 0xffff0000, v120
	s_waitcnt lgkmcnt(0)
	s_nop 1
	v_add_f32_dpp v128, v128, v128 quad_perm:[1,0,3,2] row_mask:0xf bank_mask:0xf
	v_lshlrev_b32_e32 v164, 16, v121
	v_and_b32_e32 v165, 0xffff0000, v121
	v_lshlrev_b32_e32 v156, 16, v124
	v_and_b32_e32 v157, 0xffff0000, v124
	s_waitcnt lgkmcnt(0)
	s_nop 1
	v_add_f32_dpp v129, v128, v128 quad_perm:[2,3,0,1] row_mask:0xf bank_mask:0xf
	v_lshlrev_b32_e32 v128, 16, v126
	v_lshlrev_b32_e32 v124, 16, v125
	v_and_b32_e32 v125, 0xffff0000, v125
	v_mov_b32_e32 v152, v151
	s_waitcnt lgkmcnt(0)
	s_nop 1
	v_add_f32_dpp v143, v129, v129 row_half_mirror row_mask:0xf bank_mask:0xf
	v_and_b32_e32 v129, 0xffff0000, v126
	v_lshlrev_b32_e32 v126, 16, v127
	v_and_b32_e32 v127, 0xffff0000, v127
	s_waitcnt lgkmcnt(0)
	s_nop 1
	v_add_f32_dpp v143, v143, v143 row_mirror row_mask:0xf bank_mask:0xf
	s_waitcnt lgkmcnt(0)
	v_mov_b32_e32 v150, v143
	s_nop 1
	v_permlane16_swap_b32_e32 v143, v150
	v_add_f32_e32 v143, v143, v150
	s_waitcnt lgkmcnt(0)
	v_mov_b32_e32 v122, v143
	v_mov_b32_e32 v150, v143
	s_nop 1
	v_permlane32_swap_b32_e32 v122, v150
	v_add_f32_e32 v122, v122, v150
	v_fmamk_f32 v122, v122, 0x3a800000, v142
	v_mul_f32_e32 v123, 0x4b800000, v122
	v_cmp_gt_f32_e32 vcc, s7, v122
	s_nop 1
	v_cndmask_b32_e32 v122, v122, v123, vcc
	v_rsq_f32_e32 v122, v122
	s_nop 0
	v_mul_f32_e32 v120, 0x45800000, v122
	v_cndmask_b32_e32 v150, v122, v120, vcc
	v_pk_mul_f32 v[120:121], v[150:151], v[134:135] op_sel_hi:[0,1]
	v_pk_mul_f32 v[122:123], v[150:151], v[144:145] op_sel_hi:[0,1]
	v_pk_mul_f32 v[122:123], v[0:1], v[122:123]
	v_pk_mul_f32 v[120:121], v[2:3], v[120:121]
	v_pk_fma_f32 v[122:123], v[64:65], v[128:129], v[122:123] op_sel_hi:[0,1,1]
	v_pk_fma_f32 v[120:121], v[64:65], v[126:127], v[120:121] op_sel_hi:[0,1,1]
	v_pk_mul_f32 v[126:127], v[120:121], v[120:121]
	v_pk_mul_f32 v[128:129], v[122:123], v[122:123]
	s_nop 0
	v_pk_mov_b32 v[134:135], v[128:129], v[126:127] op_sel:[1,0]
	v_mov_b32_e32 v129, v127
	v_pk_add_f32 v[126:127], v[134:135], v[128:129]
	s_nop 0
	v_pk_add_f32 v[144:145], v[126:127], v[126:127] op_sel_hi:[0,1]
	v_mov_b32_e32 v126, v147
	v_mov_b32_e32 v127, v133
	v_mov_b32_e32 v147, v132
	v_pk_mul_f32 v[126:127], v[150:151], v[126:127] op_sel_hi:[0,1]
	v_pk_mul_f32 v[128:129], v[150:151], v[146:147] op_sel_hi:[0,1]
	v_pk_mul_f32 v[128:129], v[4:5], v[128:129]
	v_pk_mul_f32 v[126:127], v[6:7], v[126:127]
	s_nop 0
	v_pk_fma_f32 v[124:125], v[64:65], v[124:125], v[126:127] op_sel_hi:[0,1,1]
	v_pk_fma_f32 v[126:127], v[64:65], v[156:157], v[128:129] op_sel_hi:[0,1,1]
	v_pk_mul_f32 v[128:129], v[124:125], v[124:125]
	v_pk_mul_f32 v[132:133], v[126:127], v[126:127]
	s_nop 0
	v_pk_mov_b32 v[134:135], v[132:133], v[128:129] op_sel:[1,0]
	v_mov_b32_e32 v133, v129
	v_pk_add_f32 v[128:129], v[134:135], v[132:133]
	v_pk_mul_f32 v[134:135], v[150:151], v[152:153] op_sel_hi:[0,1]
	v_pk_add_f32 v[146:147], v[128:129], v[128:129] op_sel_hi:[0,1]
	v_pk_mul_f32 v[128:129], v[150:151], v[130:131] op_sel_hi:[0,1]
	v_pk_mul_f32 v[130:131], v[150:151], v[148:149] op_sel_hi:[0,1]
	v_pk_mul_f32 v[130:131], v[8:9], v[130:131]
	v_pk_mul_f32 v[128:129], v[10:11], v[128:129]
	v_pk_fma_f32 v[130:131], v[64:65], v[158:159], v[130:131] op_sel_hi:[0,1,1]
	v_pk_fma_f32 v[128:129], v[64:65], v[160:161], v[128:129] op_sel_hi:[0,1,1]
	v_mul_f32_e32 v132, v130, v130
	v_pk_fma_f32 v[148:149], v[130:131], v[130:131], v[132:133] op_sel_hi:[1,1,0]
	v_mul_f32_e32 v132, v128, v128
	v_pk_fma_f32 v[156:157], v[128:129], v[128:129], v[132:133] op_sel_hi:[1,1,0]
	v_pk_mul_f32 v[132:133], v[150:151], v[154:155] op_sel_hi:[0,1]
	v_pk_mul_f32 v[134:135], v[12:13], v[134:135]
	v_pk_mul_f32 v[132:133], v[14:15], v[132:133]
	v_pk_fma_f32 v[134:135], v[64:65], v[162:163], v[134:135] op_sel_hi:[0,1,1]
	v_pk_fma_f32 v[132:133], v[64:65], v[164:165], v[132:133] op_sel_hi:[0,1,1]
	v_mul_f32_e32 v148, v134, v134
	v_mul_f32_e32 v156, v135, v135
	v_mul_f32_e32 v144, v132, v132
	v_mul_f32_e32 v146, v133, v133
	v_pk_add_f32 v[148:149], v[148:149], v[156:157]
	v_pk_add_f32 v[144:145], v[144:145], v[146:147]
	s_nop 0
	v_pk_add_f32 v[144:145], v[148:149], v[144:145]
	s_nop 0
	v_add_f32_e32 v64, v144, v145
	s_waitcnt lgkmcnt(0)
	s_nop 1
	v_add_f32_dpp v64, v64, v64 quad_perm:[1,0,3,2] row_mask:0xf bank_mask:0xf
	s_waitcnt lgkmcnt(0)
	s_nop 1
	v_add_f32_dpp v64, v64, v64 quad_perm:[2,3,0,1] row_mask:0xf bank_mask:0xf
	s_waitcnt lgkmcnt(0)
	s_nop 1
	v_add_f32_dpp v64, v64, v64 row_half_mirror row_mask:0xf bank_mask:0xf
	s_waitcnt lgkmcnt(0)
	s_nop 1
	v_add_f32_dpp v64, v64, v64 row_mirror row_mask:0xf bank_mask:0xf
	s_waitcnt lgkmcnt(0)
	v_mov_b32_e32 v143, v64
	s_nop 1
	v_permlane16_swap_b32_e32 v64, v143
	v_add_f32_e32 v64, v64, v143
	s_waitcnt lgkmcnt(0)
	v_mov_b32_e32 v143, v64
	s_nop 1
	v_permlane32_swap_b32_e32 v64, v143
	v_add_f32_e32 v64, v64, v143
	v_fmamk_f32 v64, v64, 0x3a800000, v142
	v_mul_f32_e32 v143, 0x4b800000, v64
	v_cmp_gt_f32_e32 vcc, s7, v64
	s_nop 1
	v_cndmask_b32_e32 v64, v64, v143, vcc
	v_rsq_f32_e32 v64, v64
	s_nop 0
	v_mul_f32_e32 v143, 0x45800000, v64
	v_cndmask_b32_e32 v64, v64, v143, vcc
	s_and_saveexec_b64 s[26:27], s[2:3]
	s_cbranch_execz .LBB0_584
	v_div_scale_f32 v143, s[36:37], v64, v64, 1.0
	v_rcp_f32_e32 v144, v143
	v_div_scale_f32 v145, vcc, 1.0, v64, 1.0
	s_add_u32 s24, s30, s24
	v_fma_f32 v146, -v143, v144, 1.0
	v_fmac_f32_e32 v144, v146, v144
	v_mul_f32_e32 v146, v145, v144
	v_fma_f32 v147, -v143, v146, v145
	v_fmac_f32_e32 v146, v147, v144
	v_fma_f32 v143, -v143, v146, v145
	v_div_fmas_f32 v143, v143, v144, v146
	v_div_fixup_f32 v143, v143, v64, 1.0
	s_addc_u32 s25, s31, s25
	global_store_dword v65, v143, s[24:25]

.LBB0_917:
	s_ashr_i32 s7, s6, 31
	s_lshl_b64 s[4:5], s[6:7], 11
	s_lshl_b64 s[8:9], s[6:7], 2
	s_add_u32 s8, s18, s8
	v_lshl_add_u64 v[120:121], v[68:69], 0, s[4:5]
	s_addc_u32 s9, s19, s9
	global_load_dword v64, v65, s[8:9]
	global_load_dwordx2 v[126:127], v[120:121], off nt
	global_load_dwordx2 v[124:125], v[120:121], off offset:512 nt
	global_load_dwordx2 v[122:123], v[120:121], off offset:1024 nt
	s_nop 0
	global_load_dwordx2 v[120:121], v[120:121], off offset:1536 nt
	v_lshl_add_u64 v[128:129], v[66:67], 0, s[4:5]
	global_load_dwordx2 v[134:135], v[128:129], off nt
	global_load_dwordx2 v[132:133], v[128:129], off offset:512 nt
	global_load_dwordx2 v[130:131], v[128:129], off offset:1024 nt
	s_nop 0
	global_load_dwordx2 v[128:129], v[128:129], off offset:1536 nt
	s_add_i32 s4, s6, s0
	s_cmp_lt_i32 s4, s98
	s_cselect_b64 s[10:11], -1, 0
	s_cmp_ge_i32 s4, s98
	s_cbranch_scc1 .LBB0_919
	s_ashr_i32 s5, s4, 31
	s_lshl_b64 s[12:13], s[4:5], 11
	v_lshl_add_u64 v[44:45], v[68:69], 0, s[12:13]
	s_add_u32 s8, s8, s2
	global_load_dwordx2 v[46:47], v[44:45], off nt
	global_load_dwordx2 v[52:53], v[44:45], off offset:512 nt
	global_load_dwordx2 v[54:55], v[44:45], off offset:1024 nt
	global_load_dwordx2 v[56:57], v[44:45], off offset:1536 nt
	v_lshl_add_u64 v[44:45], v[66:67], 0, s[12:13]
	s_addc_u32 s9, s9, s3
	global_load_dwordx2 v[58:59], v[44:45], off nt
	global_load_dwordx2 v[60:61], v[44:45], off offset:512 nt
	global_load_dwordx2 v[62:63], v[44:45], off offset:1024 nt
	global_load_dwordx2 v[118:119], v[44:45], off offset:1536 nt
	global_load_dword v208, v65, s[8:9]
.LBB0_919:
	s_add_i32 s8, s20, s6
	s_cmp_lt_i32 s8, s98
	s_cselect_b64 s[14:15], -1, 0
	s_cmp_ge_i32 s8, s98
	s_cbranch_scc1 .LBB0_921
	s_ashr_i32 s9, s8, 31
	s_lshl_b64 s[12:13], s[8:9], 11
	v_lshl_add_u64 v[32:33], v[68:69], 0, s[12:13]
	global_load_dwordx2 v[34:35], v[32:33], off nt
	global_load_dwordx2 v[36:37], v[32:33], off offset:512 nt
	global_load_dwordx2 v[38:39], v[32:33], off offset:1024 nt
	global_load_dwordx2 v[40:41], v[32:33], off offset:1536 nt
	v_lshl_add_u64 v[32:33], v[66:67], 0, s[12:13]
	s_lshl_b64 s[12:13], s[8:9], 2
	s_add_u32 s12, s18, s12
	s_addc_u32 s13, s19, s13
	global_load_dwordx2 v[42:43], v[32:33], off nt
	global_load_dwordx2 v[48:49], v[32:33], off offset:512 nt
	global_load_dwordx2 v[50:51], v[32:33], off offset:1024 nt
	global_load_dwordx2 v[116:117], v[32:33], off offset:1536 nt
	global_load_dword v210, v65, s[12:13]
.LBB0_921:
	s_add_i32 s12, s21, s6
	s_cmp_lt_i32 s12, s98
	s_cselect_b64 s[16:17], -1, 0
	s_cmp_ge_i32 s12, s98
	s_cbranch_scc1 .Lrl_917_w
	s_ashr_i32 s13, s12, 31
	s_lshl_b64 s[22:23], s[12:13], 11
	v_lshl_add_u64 v[16:17], v[68:69], 0, s[22:23]
	global_load_dwordx2 v[18:19], v[16:17], off nt
	global_load_dwordx2 v[20:21], v[16:17], off offset:512 nt
	global_load_dwordx2 v[22:23], v[16:17], off offset:1024 nt
	global_load_dwordx2 v[24:25], v[16:17], off offset:1536 nt
	v_lshl_add_u64 v[16:17], v[66:67], 0, s[22:23]
	s_lshl_b64 s[22:23], s[12:13], 2
	s_add_u32 s22, s18, s22
	s_addc_u32 s23, s19, s23
	global_load_dwordx2 v[26:27], v[16:17], off nt
	global_load_dwordx2 v[28:29], v[16:17], off offset:512 nt
	global_load_dwordx2 v[30:31], v[16:17], off offset:1024 nt
	global_load_dwordx2 v[108:109], v[16:17], off offset:1536 nt
	global_load_dword v212, v65, s[22:23]
.Lrl_917_w:
	s_waitcnt vmcnt(0)
	s_cmp_lg_u64 s[10:11], 0
	s_cbranch_scc0 .Lrl_917_u1
	v_lshlrev_b32_e32 v44, 16, v46
	v_and_b32_e32 v45, 0xffff0000, v46
	v_lshlrev_b32_e32 v46, 16, v47
	v_and_b32_e32 v47, 0xffff0000, v47
	v_lshlrev_b32_e32 v146, 16, v52
	v_and_b32_e32 v147, 0xffff0000, v52
	v_lshlrev_b32_e32 v52, 16, v53
	v_and_b32_e32 v53, 0xffff0000, v53
	v_lshlrev_b32_e32 v148, 16, v54
	v_and_b32_e32 v149, 0xffff0000, v54
	v_lshlrev_b32_e32 v150, 16, v55
	v_and_b32_e32 v151, 0xffff0000, v55
	v_lshlrev_b32_e32 v152, 16, v56
	v_and_b32_e32 v153, 0xffff0000, v56
	v_lshlrev_b32_e32 v154, 16, v57
	v_and_b32_e32 v155, 0xffff0000, v57
	v_lshlrev_b32_e32 v94, 16, v58
	v_and_b32_e32 v95, 0xffff0000, v58
	v_lshlrev_b32_e32 v104, 16, v59
	v_and_b32_e32 v105, 0xffff0000, v59
	v_lshlrev_b32_e32 v92, 16, v60
	v_and_b32_e32 v93, 0xffff0000, v60
	v_lshlrev_b32_e32 v110, 16, v61
	v_and_b32_e32 v111, 0xffff0000, v61
	v_lshlrev_b32_e32 v90, 16, v62
	v_and_b32_e32 v91, 0xffff0000, v62
	v_lshlrev_b32_e32 v114, 16, v63
	v_and_b32_e32 v115, 0xffff0000, v63
	v_lshlrev_b32_e32 v88, 16, v118
	v_and_b32_e32 v89, 0xffff0000, v118
	v_lshlrev_b32_e32 v118, 16, v119
	v_pk_mul_f32 v[46:47], v[208:209], v[46:47] op_sel_hi:[0,1]
	v_pk_mul_f32 v[44:45], v[208:209], v[44:45] op_sel_hi:[0,1]
	v_pk_mul_f32 v[54:55], v[208:209], v[52:53] op_sel_hi:[0,1]
	v_pk_mul_f32 v[52:53], v[208:209], v[146:147] op_sel_hi:[0,1]
	v_pk_mul_f32 v[58:59], v[208:209], v[150:151] op_sel_hi:[0,1]
	v_pk_mul_f32 v[56:57], v[208:209], v[148:149] op_sel_hi:[0,1]
	v_pk_mul_f32 v[62:63], v[208:209], v[154:155] op_sel_hi:[0,1]
	v_pk_mul_f32 v[60:61], v[208:209], v[152:153] op_sel_hi:[0,1]
	v_and_b32_e32 v119, 0xffff0000, v119
.Lrl_917_u1:
	s_cmp_lg_u64 s[14:15], 0
	s_cbranch_scc0 .Lrl_917_u2
	v_lshlrev_b32_e32 v32, 16, v34
	v_and_b32_e32 v33, 0xffff0000, v34
	v_lshlrev_b32_e32 v34, 16, v35
	v_and_b32_e32 v35, 0xffff0000, v35
	v_lshlrev_b32_e32 v146, 16, v36
	v_and_b32_e32 v147, 0xffff0000, v36
	v_lshlrev_b32_e32 v36, 16, v37
	v_and_b32_e32 v37, 0xffff0000, v37
	v_lshlrev_b32_e32 v148, 16, v38
	v_and_b32_e32 v149, 0xffff0000, v38
	v_lshlrev_b32_e32 v150, 16, v39
	v_and_b32_e32 v151, 0xffff0000, v39
	v_lshlrev_b32_e32 v152, 16, v40
	v_and_b32_e32 v153, 0xffff0000, v40
	v_lshlrev_b32_e32 v154, 16, v41
	v_and_b32_e32 v155, 0xffff0000, v41
	v_lshlrev_b32_e32 v86, 16, v42
	v_and_b32_e32 v87, 0xffff0000, v42
	v_lshlrev_b32_e32 v100, 16, v43
	v_and_b32_e32 v101, 0xffff0000, v43
	v_lshlrev_b32_e32 v84, 16, v48
	v_and_b32_e32 v85, 0xffff0000, v48
	v_lshlrev_b32_e32 v106, 16, v49
	v_and_b32_e32 v107, 0xffff0000, v49
	v_lshlrev_b32_e32 v82, 16, v50
	v_and_b32_e32 v83, 0xffff0000, v50
	v_lshlrev_b32_e32 v112, 16, v51
	v_and_b32_e32 v113, 0xffff0000, v51
	v_lshlrev_b32_e32 v80, 16, v116
	v_and_b32_e32 v81, 0xffff0000, v116
	v_lshlrev_b32_e32 v116, 16, v117
	v_pk_mul_f32 v[34:35], v[210:211], v[34:35] op_sel_hi:[0,1]
	v_pk_mul_f32 v[32:33], v[210:211], v[32:33] op_sel_hi:[0,1]
	v_pk_mul_f32 v[38:39], v[210:211], v[36:37] op_sel_hi:[0,1]
	v_pk_mul_f32 v[36:37], v[210:211], v[146:147] op_sel_hi:[0,1]
	v_pk_mul_f32 v[42:43], v[210:211], v[150:151] op_sel_hi:[0,1]
	v_pk_mul_f32 v[40:41], v[210:211], v[148:149] op_sel_hi:[0,1]
	v_pk_mul_f32 v[50:51], v[210:211], v[154:155] op_sel_hi:[0,1]
	v_pk_mul_f32 v[48:49], v[210:211], v[152:153] op_sel_hi:[0,1]
	v_and_b32_e32 v117, 0xffff0000, v117
.Lrl_917_u2:
	s_cmp_lg_u64 s[16:17], 0
	s_cbranch_scc0 .Lrl_917_u3
	v_lshlrev_b32_e32 v16, 16, v18
	v_and_b32_e32 v17, 0xffff0000, v18
	v_lshlrev_b32_e32 v18, 16, v19
	v_and_b32_e32 v19, 0xffff0000, v19
	v_lshlrev_b32_e32 v146, 16, v20
	v_and_b32_e32 v147, 0xffff0000, v20
	v_lshlrev_b32_e32 v20, 16, v21
	v_and_b32_e32 v21, 0xffff0000, v21
	v_lshlrev_b32_e32 v148, 16, v22
	v_and_b32_e32 v149, 0xffff0000, v22
	v_lshlrev_b32_e32 v150, 16, v23
	v_and_b32_e32 v151, 0xffff0000, v23
	v_lshlrev_b32_e32 v152, 16, v24
	v_and_b32_e32 v153, 0xffff0000, v24
	v_lshlrev_b32_e32 v154, 16, v25
	v_and_b32_e32 v155, 0xffff0000, v25
	v_lshlrev_b32_e32 v78, 16, v26
	v_and_b32_e32 v79, 0xffff0000, v26
	v_lshlrev_b32_e32 v96, 16, v27
	v_and_b32_e32 v97, 0xffff0000, v27
	v_lshlrev_b32_e32 v76, 16, v28
	v_and_b32_e32 v77, 0xffff0000, v28
	v_lshlrev_b32_e32 v98, 16, v29
	v_and_b32_e32 v99, 0xffff0000, v29
	v_lshlrev_b32_e32 v74, 16, v30
	v_and_b32_e32 v75, 0xffff0000, v30
	v_lshlrev_b32_e32 v102, 16, v31
	v_and_b32_e32 v103, 0xffff0000, v31
	v_lshlrev_b32_e32 v72, 16, v108
	v_and_b32_e32 v73, 0xffff0000, v108
	v_lshlrev_b32_e32 v108, 16, v109
	v_pk_mul_f32 v[18:19], v[212:213], v[18:19] op_sel_hi:[0,1]
	v_pk_mul_f32 v[16:17], v[212:213], v[16:17] op_sel_hi:[0,1]
	v_pk_mul_f32 v[22:23], v[212:213], v[20:21] op_sel_hi:[0,1]
	v_pk_mul_f32 v[20:21], v[212:213], v[146:147] op_sel_hi:[0,1]
	v_pk_mul_f32 v[26:27], v[212:213], v[150:151] op_sel_hi:[0,1]
	v_pk_mul_f32 v[24:25], v[212:213], v[148:149] op_sel_hi:[0,1]
	v_pk_mul_f32 v[30:31], v[212:213], v[154:155] op_sel_hi:[0,1]
	v_pk_mul_f32 v[28:29], v[212:213], v[152:153] op_sel_hi:[0,1]
	v_and_b32_e32 v109, 0xffff0000, v109
.Lrl_917_u3:
.LBB0_923:
	s_waitcnt vmcnt(0)
	v_lshlrev_b32_e32 v144, 16, v134
	v_and_b32_e32 v145, 0xffff0000, v134
	v_lshlrev_b32_e32 v134, 16, v135
	v_and_b32_e32 v135, 0xffff0000, v135
	v_lshlrev_b32_e32 v147, 16, v133
	v_lshlrev_b32_e32 v146, 16, v132
	v_and_b32_e32 v133, 0xffff0000, v133
	v_and_b32_e32 v132, 0xffff0000, v132
	v_lshlrev_b32_e32 v151, 16, v128
	v_and_b32_e32 v153, 0xffff0000, v128
	v_mul_f32_e32 v128, v135, v135
	v_mul_f32_e32 v150, v145, v145
	v_lshlrev_b32_e32 v154, 16, v129
	v_and_b32_e32 v155, 0xffff0000, v129
	v_pk_fma_f32 v[128:129], v[134:135], v[134:135], v[128:129] op_sel_hi:[1,1,0]
	v_pk_mul_f32 v[156:157], v[132:133], v[132:133]
	v_pk_fma_f32 v[158:159], v[144:145], v[144:145], v[150:151] op_sel_hi:[1,1,0]
	v_pk_fma_f32 v[156:157], v[146:147], v[146:147], v[156:157]
	v_mov_b32_e32 v150, v158
	v_mov_b32_e32 v160, v128
	v_mov_b32_e32 v161, v151
	v_and_b32_e32 v149, 0xffff0000, v130
	v_mul_f32_e32 v143, v153, v153
	v_pk_add_f32 v[128:129], v[158:159], v[128:129]
	v_pk_mul_f32 v[158:159], v[150:151], v[160:161]
	v_pk_add_f32 v[156:157], v[156:157], v[156:157] op_sel:[0,1] op_sel_hi:[1,0]
	v_lshlrev_b32_e32 v148, 16, v130
	v_lshlrev_b32_e32 v130, 16, v131
	v_and_b32_e32 v131, 0xffff0000, v131
	v_mov_b32_e32 v129, v159
	v_mov_b32_e32 v157, v143
	v_mul_f32_e32 v150, v149, v149
	v_pk_add_f32 v[128:129], v[128:129], v[156:157]
	v_pk_fma_f32 v[156:157], v[148:149], v[148:149], v[150:151] op_sel_hi:[1,1,0]
	v_mul_f32_e32 v150, v131, v131
	v_mul_f32_e32 v152, v154, v154
	v_mul_f32_e32 v162, v155, v155
	v_pk_fma_f32 v[158:159], v[130:131], v[130:131], v[150:151] op_sel_hi:[1,1,0]
	v_mov_b32_e32 v157, v152
	v_mov_b32_e32 v159, v162
	v_pk_add_f32 v[156:157], v[156:157], v[158:159]
	v_lshlrev_b32_e32 v158, 16, v122
	v_pk_add_f32 v[128:129], v[128:129], v[156:157]
	v_and_b32_e32 v159, 0xffff0000, v122
	v_add_f32_e32 v128, v128, v129
	v_lshlrev_b32_e32 v160, 16, v123
	v_and_b32_e32 v161, 0xffff0000, v123
	v_lshlrev_b32_e32 v162, 16, v120
	v_and_b32_e32 v163, 0xffff0000, v120
	s_waitcnt lgkmcnt(0)
	s_nop 1
	v_add_f32_dpp v128, v128, v128 quad_perm:[1,0,3,2] row_mask:0xf bank_mask:0xf
	v_lshlrev_b32_e32 v164, 16, v121
	v_and_b32_e32 v165, 0xffff0000, v121
	v_lshlrev_b32_e32 v156, 16, v124
	v_and_b32_e32 v157, 0xffff0000, v124
	s_waitcnt lgkmcnt(0)
	s_nop 1
	v_add_f32_dpp v129, v128, v128 quad_perm:[2,3,0,1] row_mask:0xf bank_mask:0xf
	v_lshlrev_b32_e32 v128, 16, v126
	v_lshlrev_b32_e32 v124, 16, v125
	v_and_b32_e32 v125, 0xffff0000, v125
	v_mov_b32_e32 v152, v151
	s_waitcnt lgkmcnt(0)
	s_nop 1
	v_add_f32_dpp v143, v129, v129 row_half_mirror row_mask:0xf bank_mask:0xf
	v_and_b32_e32 v129, 0xffff0000, v126
	v_lshlrev_b32_e32 v126, 16, v127
	v_and_b32_e32 v127, 0xffff0000, v127
	s_lshl_b64 s[6:7], s[6:7], 12
	s_waitcnt lgkmcnt(0)
	s_nop 1
	v_add_f32_dpp v143, v143, v143 row_mirror row_mask:0xf bank_mask:0xf
	s_waitcnt lgkmcnt(0)
	v_mov_b32_e32 v150, v143
	s_nop 1
	v_permlane16_swap_b32_e32 v143, v150
	v_add_f32_e32 v143, v143, v150
	s_waitcnt lgkmcnt(0)
	v_mov_b32_e32 v122, v143
	v_mov_b32_e32 v150, v143
	s_nop 1
	v_permlane32_swap_b32_e32 v122, v150
	v_add_f32_e32 v122, v122, v150
	v_fmamk_f32 v122, v122, 0x3a800000, v142
	v_mul_f32_e32 v123, 0x4b800000, v122
	v_cmp_gt_f32_e32 vcc, s1, v122
	s_nop 1
	v_cndmask_b32_e32 v122, v122, v123, vcc
	v_rsq_f32_e32 v122, v122
	s_nop 0
	v_mul_f32_e32 v120, 0x45800000, v122
	v_cndmask_b32_e32 v150, v122, v120, vcc
	v_pk_mul_f32 v[120:121], v[150:151], v[134:135] op_sel_hi:[0,1]
	v_pk_mul_f32 v[122:123], v[150:151], v[144:145] op_sel_hi:[0,1]
	v_pk_mul_f32 v[120:121], v[2:3], v[120:121]
	v_pk_mul_f32 v[134:135], v[0:1], v[122:123]
	v_pk_fma_f32 v[122:123], v[64:65], v[126:127], v[120:121] op_sel_hi:[0,1,1]
	v_mov_b32_e32 v126, v147
	v_mov_b32_e32 v127, v133
	v_mov_b32_e32 v147, v132
	v_pk_fma_f32 v[120:121], v[64:65], v[128:129], v[134:135] op_sel_hi:[0,1,1]
	v_pk_mul_f32 v[126:127], v[150:151], v[126:127] op_sel_hi:[0,1]
	v_pk_mul_f32 v[128:129], v[150:151], v[146:147] op_sel_hi:[0,1]
	v_pk_mul_f32 v[128:129], v[4:5], v[128:129]
	v_pk_mul_f32 v[126:127], v[6:7], v[126:127]
	v_pk_mul_f32 v[134:135], v[150:151], v[152:153] op_sel_hi:[0,1]
	v_pk_fma_f32 v[126:127], v[64:65], v[124:125], v[126:127] op_sel_hi:[0,1,1]
	v_pk_fma_f32 v[124:125], v[64:65], v[156:157], v[128:129] op_sel_hi:[0,1,1]
	v_pk_mul_f32 v[128:129], v[150:151], v[130:131] op_sel_hi:[0,1]
	v_pk_mul_f32 v[130:131], v[150:151], v[148:149] op_sel_hi:[0,1]
	v_pk_mul_f32 v[132:133], v[8:9], v[130:131]
	v_pk_mul_f32 v[128:129], v[10:11], v[128:129]
	v_pk_mul_f32 v[144:145], v[12:13], v[134:135]
	v_pk_fma_f32 v[130:131], v[64:65], v[160:161], v[128:129] op_sel_hi:[0,1,1]
	v_pk_fma_f32 v[128:129], v[64:65], v[158:159], v[132:133] op_sel_hi:[0,1,1]
	v_pk_mul_f32 v[132:133], v[150:151], v[154:155] op_sel_hi:[0,1]
	v_pk_mul_f32 v[132:133], v[14:15], v[132:133]
	s_andn2_b64 vcc, exec, s[10:11]
	v_pk_fma_f32 v[134:135], v[64:65], v[164:165], v[132:133] op_sel_hi:[0,1,1]
	v_pk_fma_f32 v[132:133], v[64:65], v[162:163], v[144:145] op_sel_hi:[0,1,1]
	v_lshl_add_u64 v[144:145], v[70:71], 0, s[6:7]
	global_store_dwordx4 v[144:145], v[120:123], off nt
	global_store_dwordx4 v[144:145], v[124:127], off offset:1024 nt
	global_store_dwordx4 v[144:145], v[128:131], off offset:2048 nt
	global_store_dwordx4 v[144:145], v[132:135], off offset:3072 nt
	s_cbranch_vccz .LBB0_926
	s_andn2_b64 vcc, exec, s[14:15]
	s_cbranch_vccz .LBB0_927
